# NSA loops: drop NaN-canonicalising v_max pairs on the mask fast path and replace the more-mask ballot recompute by s_not_b64
# baseline (speedup 1.0000x reference)
.LBB0_1208:
	s_not_b64 s[14:15], s[0:1]
	s_andn2_b64 vcc, exec, s[0:1]
	s_waitcnt lgkmcnt(0)
	v_ashrrev_i32_e32 v15, 31, v14
	v_readfirstlane_b32 s99, v14
	s_cbranch_vccnz .LBB0_1210
	s_waitcnt vmcnt(1)
	v_lshlrev_b64 v[2:3], 14, v[14:15]
	v_lshl_add_u64 v[2:3], v[174:175], 0, v[2:3]
	s_waitcnt vmcnt(0)
	v_add_co_u32_e32 v6, vcc, 0x2000, v2
	s_nop 1
	v_addc_co_u32_e32 v7, vcc, 0, v3, vcc
	global_load_dwordx4 v[2:5], v[2:3], off
	s_nop 0
	global_load_dwordx4 v[6:9], v[6:7], off

.Lself0:
	v_cndmask_b32_e64 v237, v231, v82, s[16:17]
	v_cndmask_b32_e64 v238, v231, v83, s[16:17]
	v_cndmask_b32_e64 v239, v231, v84, s[16:17]
	v_cndmask_b32_e64 v240, v231, v85, s[16:17]
	v_cndmask_b32_e64 v142, v231, v86, s[16:17]
	v_cndmask_b32_e64 v143, v231, v87, s[16:17]
	v_cndmask_b32_e64 v144, v231, v88, s[16:17]
	v_cndmask_b32_e64 v145, v231, v89, s[16:17]
	v_cndmask_b32_e64 v244, v231, v90, s[16:17]
	v_cndmask_b32_e64 v241, v231, v91, s[16:17]
	v_cndmask_b32_e64 v242, v231, v92, s[16:17]
	v_cndmask_b32_e64 v243, v231, v93, s[16:17]
	v_cndmask_b32_e64 v90, v231, v94, s[16:17]
	v_cndmask_b32_e64 v91, v231, v95, s[16:17]
	v_cndmask_b32_e64 v92, v231, v96, s[16:17]
	v_max_f32_e32 v0, v237, v238
	v_max3_f32 v0, v0, v239, v240
	v_max3_f32 v0, v0, v142, v143
	v_max3_f32 v0, v0, v144, v145
	v_max3_f32 v0, v0, v244, v241
	v_max3_f32 v0, v0, v242, v243
	v_cndmask_b32_e64 v93, v231, v97, s[16:17]
	v_max3_f32 v0, v0, v90, v91
	v_max3_f32 v0, v0, v92, v93
	s_branch .Lself0_join
.Lself1:
	v_cndmask_b32_e64 v144, v231, v82, s[16:17]
	v_cndmask_b32_e64 v145, v231, v83, s[16:17]
	v_cndmask_b32_e64 v233, v231, v84, s[16:17]
	v_cndmask_b32_e64 v234, v231, v85, s[16:17]
	v_cndmask_b32_e64 v14, v231, v86, s[16:17]
	v_cndmask_b32_e64 v15, v231, v87, s[16:17]
	v_cndmask_b32_e64 v142, v231, v88, s[16:17]
	v_cndmask_b32_e64 v143, v231, v89, s[16:17]
	v_cndmask_b32_e64 v237, v231, v90, s[16:17]
	v_cndmask_b32_e64 v238, v231, v91, s[16:17]
	v_cndmask_b32_e64 v239, v231, v92, s[16:17]
	v_cndmask_b32_e64 v240, v231, v93, s[16:17]
	v_cndmask_b32_e64 v90, v231, v94, s[16:17]
	v_cndmask_b32_e64 v91, v231, v95, s[16:17]
	v_cndmask_b32_e64 v92, v231, v96, s[16:17]
	v_max_f32_e32 v0, v144, v145
	v_max3_f32 v0, v0, v233, v234
	v_max3_f32 v0, v0, v14, v15
	v_max3_f32 v0, v0, v142, v143
	v_max3_f32 v0, v0, v237, v238
	v_max3_f32 v0, v0, v239, v240
	v_cndmask_b32_e64 v93, v231, v97, s[16:17]
	v_max3_f32 v0, v0, v90, v91
	v_max3_f32 v0, v0, v92, v93
	s_branch .Lself1_join

.LBB0_1236:
	s_not_b64 s[12:13], s[0:1]
	s_andn2_b64 vcc, exec, s[0:1]
	v_ashrrev_i32_e32 v15, 31, v14
	s_cbranch_vccnz .LBB0_1238
	s_waitcnt vmcnt(1)
	v_lshlrev_b64 v[2:3], 14, v[14:15]
	v_lshl_add_u64 v[2:3], v[168:169], 0, v[2:3]
	s_waitcnt vmcnt(0)
	v_add_co_u32_e32 v6, vcc, 0x2000, v2
	s_nop 1
	v_addc_co_u32_e32 v7, vcc, 0, v3, vcc
	global_load_dwordx4 v[2:5], v[2:3], off
	s_nop 0
	global_load_dwordx4 v[6:9], v[6:7], off

.Lwinf0:
	v_mov_b32_e32 v143, v80
	v_mov_b32_e32 v144, v81
	v_mov_b32_e32 v145, v82
	v_mov_b32_e32 v232, v83
	v_mov_b32_e32 v233, v84
	v_mov_b32_e32 v234, v85
	v_mov_b32_e32 v235, v86
	v_mov_b32_e32 v236, v87
	v_max_f32_e32 v0, v143, v144
	v_max3_f32 v0, v0, v145, v232
	v_max3_f32 v0, v0, v233, v234
	v_max3_f32 v0, v0, v235, v236
	v_max3_f32 v0, v0, v88, v89
	v_max3_f32 v0, v0, v90, v91
	v_max3_f32 v0, v0, v92, v93
	v_max3_f32 v0, v0, v94, v95
	s_branch .Lwinf0_join
.Lwinf1:
	v_mov_b32_e32 v15, v80
	v_mov_b32_e32 v143, v81
	v_mov_b32_e32 v144, v82
	v_mov_b32_e32 v145, v83
	v_mov_b32_e32 v245, v84
	v_mov_b32_e32 v247, v85
	v_mov_b32_e32 v248, v86
	v_mov_b32_e32 v249, v87
	v_max_f32_e32 v14, v15, v143
	v_max3_f32 v14, v14, v144, v145
	v_max3_f32 v14, v14, v245, v247
	v_max3_f32 v14, v14, v248, v249
	v_max3_f32 v14, v14, v88, v89
	v_max3_f32 v14, v14, v90, v91
	v_max3_f32 v14, v14, v92, v93
	v_max3_f32 v14, v14, v94, v95
	s_branch .Lwinf1_join
